# v13 + all late micro-edits stacked: K-loop mid-segment setprio pairs removed, attention QK fragment reads pipelined in place, -inf constant fold in softmax mask code
# speedup vs baseline: 1.0040x; 1.0040x over previous
; #define LAS __attribute__((address_space(3)))
; __device__ __forceinline__ void attn_unit(LAS unsigned char* lds, bf16_t* proj, const float* biasG, const float* sink, int s, int qb, int kh, int hp, bf16_t* dummy = nullptr) {
;     ...
;             if (st < wq || st > wq + 8) continue;
;             f32x4 sa[2][2];
; #pragma unroll
;             for (int kt = 0; kt < 2; ++kt) { sa[kt][0] = (f32x4){0.f, 0.f, 0.f, 0.f}; sa[kt][1] = (f32x4){0.f, 0.f, 0.f, 0.f}; }
; #pragma unroll
;             for (int ks = 0; ks < 4; ++ks)
; #pragma unroll
;                 for (int kt = 0; kt < 2; ++kt) {
;                     const bf16x8 kf = *(const LAS bf16x8*)(Ks + (si * 32 + kt * 16 + l16) * 272 + ks * 64 + kg * 16);
;                     sa[kt][0] = __builtin_amdgcn_mfma_f32_16x16x32_bf16(kf, qf[0][ks], sa[kt][0], 0, 0, 0);
;                     sa[kt][1] = __builtin_amdgcn_mfma_f32_16x16x32_bf16(kf, qf[1][ks], sa[kt][1], 0, 0, 0);
;                 }
;             bf16x8 pf[2];
; #pragma unroll
;             for (int qt = 0; qt < 2; ++qt) {
;                 const int qp = wq * 32 + qt * 16 + l16;
;                 float sv[8]; float mx = -1e30f;
; #pragma unroll
;                 for (int kt = 0; kt < 2; ++kt)
; #pragma unroll
;                     for (int r = 0; r < 4; ++r) {
;                         const int kp = (kbi - 1) * 128 + si * 32 + kt * 16 + kg * 4 + r;
;                         const int rel = kp - qp; const bool valid = (rel >= -128) && (rel <= 128);
;                         const int idx = min(max(rel + 128, 0), 256);
;                         const float v = valid ? (sa[kt][qt][r] * SC + bL[hl * 260 + idx]) : -1e30f;
;                         sv[kt * 4 + r] = v; mx = fmaxf(mx, v);
;                     }
;                 mx = fmaxf(mx, __shfl_xor(mx, 16)); mx = fmaxf(mx, __shfl_xor(mx, 32));
.LBB0_665:
	s_add_i32 s19, s30, -3
	v_cmp_ge_u32_e32 vcc, s19, v192
	v_cmp_le_u32_e64 s[4:5], s19, v195
	s_and_b64 s[4:5], vcc, s[4:5]
	s_and_saveexec_b64 s[74:75], s[4:5]
	s_cbranch_execz .LBB0_699
	v_add_u32_e32 v251, 0x11700, v200
	v_add_u32_e32 v251, v251, v196
	v_add_u32_e32 v252, 0x11700, v201
	v_add_u32_e32 v252, v252, v196
	ds_read_b32 v235, v252 offset:256
	ds_read_b32 v236, v252 offset:260
	ds_read_b32 v237, v252 offset:264
	ds_read_b32 v238, v252 offset:268
	ds_read_b32 v239, v252 offset:320
	ds_read_b32 v240, v252 offset:324
	ds_read_b32 v241, v252 offset:328
	ds_read_b32 v242, v252 offset:332
	ds_read_b32 v243, v251 offset:192
	ds_read_b32 v244, v251 offset:196
	ds_read_b32 v245, v251 offset:200
	ds_read_b32 v246, v251 offset:204
	ds_read_b32 v247, v252 offset:256
	ds_read_b32 v248, v252 offset:260
	ds_read_b32 v249, v252 offset:264
	ds_read_b32 v250, v252 offset:268
	ds_read_b128 v[140:143], v213
	ds_read_b128 v[132:135], v213 offset:4352
	ds_read_b128 v[226:229], v213 offset:64
	ds_read_b128 v[230:233], v213 offset:4416
	v_add_u32_e32 v1, 0xffffff8d, v199
	v_cmp_gt_u32_e32 vcc, s53, v1
	v_add3_u32 v2, v201, v196, s31
	s_waitcnt lgkmcnt(3)
	v_mfma_f32_16x16x32_bf16 v[144:147], v[140:143], v[4:7], 0
	v_mfma_f32_16x16x32_bf16 v[140:143], v[140:143], v[20:23], 0
	s_waitcnt lgkmcnt(2)
	v_mfma_f32_16x16x32_bf16 v[136:139], v[132:135], v[20:23], 0
	v_mfma_f32_16x16x32_bf16 v[132:135], v[132:135], v[4:7], 0
	s_waitcnt lgkmcnt(1)
	v_mfma_f32_16x16x32_bf16 v[144:147], v[226:229], v[8:11], v[144:147]
	v_mfma_f32_16x16x32_bf16 v[140:143], v[226:229], v[24:27], v[140:143]
	ds_read_b128 v[226:229], v213 offset:128
	s_waitcnt lgkmcnt(1)
	v_mfma_f32_16x16x32_bf16 v[132:135], v[230:233], v[8:11], v[132:135]
	v_mfma_f32_16x16x32_bf16 v[136:139], v[230:233], v[24:27], v[136:139]
	ds_read_b128 v[230:233], v213 offset:4480
	s_waitcnt lgkmcnt(1)
	v_mfma_f32_16x16x32_bf16 v[144:147], v[226:229], v[12:15], v[144:147]
	v_mfma_f32_16x16x32_bf16 v[140:143], v[226:229], v[28:31], v[140:143]
	ds_read_b128 v[226:229], v213 offset:192
	s_waitcnt lgkmcnt(1)
	v_mfma_f32_16x16x32_bf16 v[132:135], v[230:233], v[12:15], v[132:135]
	v_mfma_f32_16x16x32_bf16 v[136:139], v[230:233], v[28:31], v[136:139]
	ds_read_b128 v[230:233], v213 offset:4544
	s_waitcnt lgkmcnt(1)
	v_mfma_f32_16x16x32_bf16 v[144:147], v[226:229], v[16:19], v[144:147]
	v_mfma_f32_16x16x32_bf16 v[140:143], v[226:229], v[32:35], v[140:143]
	s_waitcnt lgkmcnt(0)
	v_mfma_f32_16x16x32_bf16 v[132:135], v[230:233], v[16:19], v[132:135]
	v_mfma_f32_16x16x32_bf16 v[136:139], v[230:233], v[32:35], v[136:139]
	s_nop 2
	v_mov_b32_e32 v251, 0xf149f2ca
	s_waitcnt lgkmcnt(0)
	v_fmac_f32_e32 v235, 0x3e0293ee, v144
	v_cndmask_b32_e32 v229, v251, v235, vcc
	v_add_u32_e32 v1, 0xffffff8e, v199
	v_cmp_gt_u32_e64 s[4:5], s53, v1
	v_add3_u32 v225, v201, v196, s40
	v_fmac_f32_e32 v236, 0x3e0293ee, v145
	v_cndmask_b32_e64 v228, v251, v236, s[4:5]
	v_add_u32_e32 v1, 0xffffff8f, v199
	v_cmp_gt_u32_e64 s[6:7], s53, v1
	v_add3_u32 v226, v201, v196, s42
	v_fmac_f32_e32 v237, 0x3e0293ee, v146
	v_cndmask_b32_e64 v230, v251, v237, s[6:7]
	v_add_u32_e32 v1, 0xffffff90, v199
	v_cmp_gt_u32_e64 s[8:9], s53, v1
	v_add3_u32 v227, v201, v196, s96
	v_fmac_f32_e32 v238, 0x3e0293ee, v147
	v_cndmask_b32_e64 v145, v251, v238, s[8:9]
	v_add_u32_e32 v1, 0xffffff9d, v199
	v_cmp_gt_u32_e64 s[10:11], s53, v1
	v_fmac_f32_e32 v239, 0x3e0293ee, v132
	s_nop 0
	v_cndmask_b32_e64 v231, v251, v239, s[10:11]
	v_add_u32_e32 v1, 0xffffff9e, v199
	v_cmp_gt_u32_e64 s[10:11], s53, v1
	v_fmac_f32_e32 v240, 0x3e0293ee, v133
	s_nop 0
	v_cndmask_b32_e64 v232, v251, v240, s[10:11]
	v_add_u32_e32 v1, 0xffffff9f, v199
	v_cmp_gt_u32_e64 s[10:11], s53, v1
	v_fmac_f32_e32 v241, 0x3e0293ee, v134
	s_nop 0
	v_cndmask_b32_e64 v133, v251, v241, s[10:11]
	v_add_u32_e32 v1, 0xffffffa0, v199
	v_cmp_gt_u32_e64 s[10:11], s53, v1
	v_fmac_f32_e32 v242, 0x3e0293ee, v135
	s_nop 0
	v_cndmask_b32_e64 v132, v251, v242, s[10:11]
	v_mov_b32_e32 v144, 0xf149f2ca
	v_and_b32_e32 v134, 64, v182
	v_max3_f32 v1, v229, v144, v228
	v_xor_b32_e32 v3, 16, v182
	v_add_u32_e32 v134, 64, v134
	v_max3_f32 v1, v1, v230, v145
	v_cmp_lt_i32_e64 s[10:11], v3, v134
	v_max3_f32 v1, v1, v231, v232
	v_max3_f32 v1, v1, v133, v132
	v_cndmask_b32_e64 v3, v182, v3, s[10:11]
	v_lshlrev_b32_e32 v146, 2, v3
	v_mov_b32_e32 v253, v1
	v_mov_b32_e32 v135, v1
	s_nop 1
	v_permlane16_swap_b32_e32 v253, v135
	v_max_f32_e32 v135, v135, v253
	v_xor_b32_e32 v3, 32, v182
	v_cmp_lt_i32_e64 s[10:11], v3, v134
	s_waitcnt lgkmcnt(0)
	v_max_f32_e32 v134, v135, v135
	v_cndmask_b32_e64 v3, v182, v3, s[10:11]
	v_lshlrev_b32_e32 v3, 2, v3
	v_max_f32_e32 v1, v1, v134
	v_mov_b32_e32 v253, v1
	v_mov_b32_e32 v134, v1
	s_nop 1
	v_permlane32_swap_b32_e32 v253, v134
	v_max_f32_e32 v134, v134, v253
	s_waitcnt lgkmcnt(0)
; #define LAS __attribute__((address_space(3)))
; __device__ __forceinline__ unsigned cvt_pk_bf16(float lo, float hi) { unsigned r; asm volatile("v_cvt_pk_bf16_f32 %0, %1, %2" : "=v"(r) : "v"(lo), "v"(hi)); return r; }
; __device__ __forceinline__ void attn_unit(LAS unsigned char* lds, bf16_t* proj, const float* biasG, const float* sink, int s, int qb, int kh, int hp, bf16_t* dummy = nullptr) {
;     ...
;                     for (int r = 0; r < 4; ++r) {
;                         const int kp = (kbi - 1) * 128 + si * 32 + kt * 16 + kg * 4 + r;
;                         const int rel = kp - qp; const bool valid = (rel >= -128) && (rel <= 128);
;                         const int idx = min(max(rel + 128, 0), 256);
;                         const float v = valid ? (sa[kt][qt][r] * SC + bL[hl * 260 + idx]) : -1e30f;
;                         sv[kt * 4 + r] = v; mx = fmaxf(mx, v);
;                     }
;                 mx = fmaxf(mx, __shfl_xor(mx, 16)); mx = fmaxf(mx, __shfl_xor(mx, 32));
;                 const float mnew = fmaxf(m2[qt], mx), alpha = __builtin_amdgcn_exp2f(m2[qt] - mnew); m2[qt] = mnew;
;                 float ps = 0.f; float pv[8];
; #pragma unroll
;                 for (int i = 0; i < 8; ++i) { pv[i] = __builtin_amdgcn_exp2f(sv[i] - mnew); ps += pv[i]; }
;                 lsum[qt] = lsum[qt] * alpha + ps;
; #pragma unroll
;                 for (int dt = 0; dt < 8; ++dt) o[dt][qt] = o[dt][qt] * alpha;
;                 u32x4 pw; pw.x = cvt_pk_bf16(pv[0], pv[1]); pw.y = cvt_pk_bf16(pv[2], pv[3]); pw.z = cvt_pk_bf16(pv[4], pv[5]); pw.w = cvt_pk_bf16(pv[6], pv[7]);
;                 pf[qt] = __builtin_bit_cast(bf16x8, pw);
;             }
; #pragma unroll
;             for (int dt = 0; dt < 8; ++dt) {
;                 const LAS unsigned char* vr = Vt + (dt * 16 + l16) * 288 + (si * 32 + kg * 4) * 2;
;                 const u32x2 lo = *(const LAS u32x2*)(vr), hi = *(const LAS u32x2*)(vr + 32);
	v_max3_f32 v1, v224, v1, v134
	v_sub_f32_e32 v134, v229, v1
	v_exp_f32_e32 v147, v134
	v_sub_f32_e32 v134, v228, v1
	v_exp_f32_e32 v228, v134
	v_sub_f32_e32 v134, v230, v1
	v_exp_f32_e32 v229, v134
	v_sub_f32_e32 v134, v145, v1
	v_exp_f32_e32 v230, v134
	v_sub_f32_e32 v134, v231, v1
	v_exp_f32_e32 v231, v134
	v_sub_f32_e32 v134, v232, v1
	v_sub_f32_e32 v133, v133, v1
	v_sub_f32_e32 v132, v132, v1
	v_exp_f32_e32 v232, v134
	v_exp_f32_e32 v233, v133
	v_exp_f32_e32 v234, v132
	v_add_u32_e32 v145, 0xffffff7d, v199
	v_cmp_gt_u32_e64 s[10:11], s53, v145
	v_cvt_pk_bf16_f32 v132, v147, v228
	v_cvt_pk_bf16_f32 v133, v229, v230
	v_cvt_pk_bf16_f32 v134, v231, v232
	v_cvt_pk_bf16_f32 v135, v233, v234
	v_fmac_f32_e32 v243, 0x3e0293ee, v140
	v_cndmask_b32_e64 v145, v251, v243, s[10:11]
	v_add_u32_e32 v140, 0xffffff7e, v199
	v_cmp_gt_u32_e64 s[10:11], s53, v140
	v_fmac_f32_e32 v244, 0x3e0293ee, v141
	s_nop 0
	v_cndmask_b32_e64 v144, v144, v244, s[10:11]
	v_add_u32_e32 v140, 0xffffff7f, v199
	v_cmp_gt_u32_e64 s[10:11], s53, v140
	v_fmac_f32_e32 v245, 0x3e0293ee, v142
	s_nop 0
	v_cndmask_b32_e64 v141, v251, v245, s[10:11]
	v_add_u32_e32 v142, 0xffffff80, v199
	v_cmp_gt_u32_e64 s[10:11], s53, v142
	v_fmac_f32_e32 v246, 0x3e0293ee, v143
	s_nop 0
	v_cndmask_b32_e64 v140, v251, v246, s[10:11]
	v_fmac_f32_e32 v247, 0x3e0293ee, v136
	v_cndmask_b32_e32 v143, v251, v247, vcc
	v_fmac_f32_e32 v248, 0x3e0293ee, v137
	v_cndmask_b32_e64 v142, v251, v248, s[4:5]
	v_fmac_f32_e32 v249, 0x3e0293ee, v138
	v_cndmask_b32_e64 v137, v251, v249, s[6:7]
	v_fmac_f32_e32 v250, 0x3e0293ee, v139
	v_cndmask_b32_e64 v136, v251, v250, s[8:9]
	v_max3_f32 v2, v145, s89, v144
	v_max3_f32 v2, v2, v141, v140
	v_max3_f32 v139, v2, v143, v142
	v_add_f32_e32 v2, 0, v147
	v_add_f32_e32 v2, v228, v2
	v_add_f32_e32 v2, v229, v2
	v_sub_f32_e32 v138, v224, v1
	v_add_f32_e32 v2, v230, v2
	v_add_f32_e32 v2, v231, v2
	v_exp_f32_e32 v138, v138
	v_add_f32_e32 v2, v232, v2
	v_add_f32_e32 v2, v233, v2
	v_add_f32_e32 v2, v234, v2
	v_fmac_f32_e32 v2, v223, v138
	v_pk_mul_f32 v[98:99], v[98:99], v[138:139] op_sel_hi:[1,0]
	v_pk_mul_f32 v[96:97], v[96:97], v[138:139] op_sel_hi:[1,0]
	v_pk_mul_f32 v[106:107], v[106:107], v[138:139] op_sel_hi:[1,0]
	v_pk_mul_f32 v[104:105], v[104:105], v[138:139] op_sel_hi:[1,0]
	v_pk_mul_f32 v[110:111], v[110:111], v[138:139] op_sel_hi:[1,0]
	v_pk_mul_f32 v[108:109], v[108:109], v[138:139] op_sel_hi:[1,0]
	v_pk_mul_f32 v[114:115], v[114:115], v[138:139] op_sel_hi:[1,0]
	v_pk_mul_f32 v[112:113], v[112:113], v[138:139] op_sel_hi:[1,0]
	v_pk_mul_f32 v[118:119], v[118:119], v[138:139] op_sel_hi:[1,0]
	v_pk_mul_f32 v[116:117], v[116:117], v[138:139] op_sel_hi:[1,0]
	v_pk_mul_f32 v[122:123], v[122:123], v[138:139] op_sel_hi:[1,0]
	v_pk_mul_f32 v[120:121], v[120:121], v[138:139] op_sel_hi:[1,0]
	v_pk_mul_f32 v[126:127], v[126:127], v[138:139] op_sel_hi:[1,0]
	v_pk_mul_f32 v[124:125], v[124:125], v[138:139] op_sel_hi:[1,0]
	v_pk_mul_f32 v[130:131], v[130:131], v[138:139] op_sel_hi:[1,0]
	v_pk_mul_f32 v[128:129], v[128:129], v[138:139] op_sel_hi:[1,0]
	v_max3_f32 v138, v139, v137, v136
	v_mov_b32_e32 v253, v138
	v_mov_b32_e32 v139, v138
	s_nop 1
	v_permlane16_swap_b32_e32 v253, v139
	v_max_f32_e32 v139, v139, v253
	v_mov_b32_e32 v223, v2
	v_mov_b32_e32 v224, v1
	s_waitcnt lgkmcnt(0)
	v_max_f32_e32 v139, v139, v139
	v_max_f32_e32 v138, v138, v139
	v_mov_b32_e32 v253, v138
	v_mov_b32_e32 v3, v138
	s_nop 1
	v_permlane32_swap_b32_e32 v253, v3
	v_max_f32_e32 v3, v3, v253
	s_waitcnt lgkmcnt(0)
	v_max3_f32 v3, v222, v138, v3
	v_sub_f32_e32 v139, v145, v3
	v_exp_f32_e32 v139, v139
	v_sub_f32_e32 v144, v144, v3
	v_exp_f32_e32 v144, v144
	v_sub_f32_e32 v141, v141, v3
	v_exp_f32_e32 v141, v141
	v_sub_f32_e32 v140, v140, v3
	v_exp_f32_e32 v146, v140
	v_add_f32_e32 v145, 0, v139
	v_sub_f32_e32 v143, v143, v3
	v_add_f32_e32 v145, v144, v145
	v_exp_f32_e32 v143, v143
	v_sub_f32_e32 v142, v142, v3
	v_add_f32_e32 v145, v141, v145
	v_exp_f32_e32 v142, v142
	v_sub_f32_e32 v137, v137, v3
	v_add_f32_e32 v140, v146, v145
	v_exp_f32_e32 v145, v137
	v_sub_f32_e32 v136, v136, v3
	v_sub_f32_e32 v138, v222, v3
	v_exp_f32_e32 v147, v136
	v_add_f32_e32 v140, v143, v140
	v_exp_f32_e32 v136, v138
	v_add_f32_e32 v140, v142, v140
	v_add_f32_e32 v137, v145, v140
	v_add_f32_e32 v140, v147, v137
	v_fmac_f32_e32 v140, v221, v136
	v_pk_mul_f32 v[70:71], v[70:71], v[136:137] op_sel_hi:[1,0]
	v_pk_mul_f32 v[68:69], v[68:69], v[136:137] op_sel_hi:[1,0]
	v_pk_mul_f32 v[74:75], v[74:75], v[136:137] op_sel_hi:[1,0]
	v_pk_mul_f32 v[72:73], v[72:73], v[136:137] op_sel_hi:[1,0]
	v_pk_mul_f32 v[78:79], v[78:79], v[136:137] op_sel_hi:[1,0]
	v_pk_mul_f32 v[76:77], v[76:77], v[136:137] op_sel_hi:[1,0]
	v_pk_mul_f32 v[82:83], v[82:83], v[136:137] op_sel_hi:[1,0]
	v_pk_mul_f32 v[80:81], v[80:81], v[136:137] op_sel_hi:[1,0]
	v_pk_mul_f32 v[86:87], v[86:87], v[136:137] op_sel_hi:[1,0]
	v_pk_mul_f32 v[84:85], v[84:85], v[136:137] op_sel_hi:[1,0]
	v_pk_mul_f32 v[90:91], v[90:91], v[136:137] op_sel_hi:[1,0]
	v_pk_mul_f32 v[88:89], v[88:89], v[136:137] op_sel_hi:[1,0]
	v_pk_mul_f32 v[94:95], v[94:95], v[136:137] op_sel_hi:[1,0]
	v_pk_mul_f32 v[92:93], v[92:93], v[136:137] op_sel_hi:[1,0]
	v_pk_mul_f32 v[102:103], v[102:103], v[136:137] op_sel_hi:[1,0]
	v_pk_mul_f32 v[100:101], v[100:101], v[136:137] op_sel_hi:[1,0]
	v_cvt_pk_bf16_f32 v136, v139, v144
	v_cvt_pk_bf16_f32 v137, v141, v146
	v_add_u32_e32 v141, v197, v198
	v_cvt_pk_bf16_f32 v138, v143, v142
	v_add_u32_e32 v142, 0x8800, v141
	v_cvt_pk_bf16_f32 v139, v145, v147
	ds_read2_b64 v[236:239], v142 offset1:4
	v_mov_b32_e32 v221, v140
	v_add_u32_e32 v252, 0x9800, v141
	ds_read2_b64 v[240:243], v252 offset0:64 offset1:68
	v_add_u32_e32 v252, 0xa800, v141
	ds_read2_b64 v[244:247], v252 offset0:128 offset1:132
	v_add_u32_e32 v252, 0xb800, v141
	ds_read2_b64 v[248:251], v252 offset0:192 offset1:196
	s_waitcnt lgkmcnt(3)
; __device__ __forceinline__ void attn_unit(LAS unsigned char* lds, bf16_t* proj, const float* biasG, const float* sink, int s, int qb, int kh, int hp, bf16_t* dummy = nullptr) {
;     ...
;             if (st < wq || st > wq + 8) continue;
;             f32x4 sa[2][2];
; #pragma unroll
;             for (int kt = 0; kt < 2; ++kt) { sa[kt][0] = (f32x4){0.f, 0.f, 0.f, 0.f}; sa[kt][1] = (f32x4){0.f, 0.f, 0.f, 0.f}; }
; #pragma unroll
;             for (int ks = 0; ks < 4; ++ks)
; #pragma unroll
;                 for (int kt = 0; kt < 2; ++kt) {
;                     const bf16x8 kf = *(const LAS bf16x8*)(Ks + (si * 32 + kt * 16 + l16) * 272 + ks * 64 + kg * 16);
;                     sa[kt][0] = __builtin_amdgcn_mfma_f32_16x16x32_bf16(kf, qf[0][ks], sa[kt][0], 0, 0, 0);
;                     sa[kt][1] = __builtin_amdgcn_mfma_f32_16x16x32_bf16(kf, qf[1][ks], sa[kt][1], 0, 0, 0);
;                 }
;             bf16x8 pf[2];
; #pragma unroll
;             for (int qt = 0; qt < 2; ++qt) {
;                 const int qp = wq * 32 + qt * 16 + l16;
;                 float sv[8]; float mx = -1e30f;
; #pragma unroll
;                 for (int kt = 0; kt < 2; ++kt)
; #pragma unroll
;                     for (int r = 0; r < 4; ++r) {
;                         const int kp = (kbi - 1) * 128 + si * 32 + kt * 16 + kg * 4 + r;
;                         const int rel = kp - qp; const bool valid = (rel >= -128) && (rel <= 128);
;                         const int idx = min(max(rel + 128, 0), 256);
;                         const float v = valid ? (sa[kt][qt][r] * SC + bL[hl * 260 + idx]) : -1e30f;
;                         sv[kt * 4 + r] = v; mx = fmaxf(mx, v);
;                     }
;                 mx = fmaxf(mx, __shfl_xor(mx, 16)); mx = fmaxf(mx, __shfl_xor(mx, 32));
;     ...
;             for (int dt = 0; dt < 8; ++dt) {
;                 const LAS unsigned char* vr = Vt + (dt * 16 + l16) * 288 + (si * 32 + kg * 4) * 2;
;                 const u32x2 lo = *(const LAS u32x2*)(vr), hi = *(const LAS u32x2*)(vr + 32);
;                 u32x4 vw; vw.x = lo.x; vw.y = lo.y; vw.z = hi.x; vw.w = hi.y;
;                 const bf16x8 vf = __builtin_bit_cast(bf16x8, vw);
;                 o[dt][0] = __builtin_amdgcn_mfma_f32_16x16x32_bf16(vf, pf[0], o[dt][0], 0, 0, 0);
;                 o[dt][1] = __builtin_amdgcn_mfma_f32_16x16x32_bf16(vf, pf[1], o[dt][1], 0, 0, 0);
;             }
	v_mfma_f32_16x16x32_bf16 v[96:99], v[236:239], v[132:135], v[96:99]
	v_mov_b32_e32 v222, v3
	v_mfma_f32_16x16x32_bf16 v[68:71], v[236:239], v[136:139], v[68:71]
	v_add_u32_e32 v252, 0xd000, v141
	ds_read2_b64 v[236:239], v252 offset1:4
	s_waitcnt lgkmcnt(3)
	v_mfma_f32_16x16x32_bf16 v[104:107], v[240:243], v[132:135], v[104:107]
	v_mfma_f32_16x16x32_bf16 v[72:75], v[240:243], v[136:139], v[72:75]
	v_add_u32_e32 v252, 0xe000, v141
	ds_read2_b64 v[240:243], v252 offset0:64 offset1:68
	v_add_u32_e32 v141, 0xf000, v141
	s_waitcnt lgkmcnt(3)
	v_mfma_f32_16x16x32_bf16 v[108:111], v[244:247], v[132:135], v[108:111]
	v_mfma_f32_16x16x32_bf16 v[76:79], v[244:247], v[136:139], v[76:79]
	ds_read2_b64 v[244:247], v141 offset0:128 offset1:132
	s_waitcnt lgkmcnt(3)
	v_mfma_f32_16x16x32_bf16 v[112:115], v[248:251], v[132:135], v[112:115]
	v_mfma_f32_16x16x32_bf16 v[80:83], v[248:251], v[136:139], v[80:83]
	ds_read2_b64 v[248:251], v214 offset0:192 offset1:196
	s_waitcnt lgkmcnt(3)
	v_mfma_f32_16x16x32_bf16 v[116:119], v[236:239], v[132:135], v[116:119]
	v_mfma_f32_16x16x32_bf16 v[84:87], v[236:239], v[136:139], v[84:87]
	s_waitcnt lgkmcnt(2)
	v_mfma_f32_16x16x32_bf16 v[120:123], v[240:243], v[132:135], v[120:123]
	v_mfma_f32_16x16x32_bf16 v[88:91], v[240:243], v[136:139], v[88:91]
	s_waitcnt lgkmcnt(1)
	v_mfma_f32_16x16x32_bf16 v[124:127], v[244:247], v[132:135], v[124:127]
	v_mfma_f32_16x16x32_bf16 v[92:95], v[244:247], v[136:139], v[92:95]
	s_waitcnt lgkmcnt(0)
	v_mfma_f32_16x16x32_bf16 v[128:131], v[248:251], v[132:135], v[128:131]
	v_mfma_f32_16x16x32_bf16 v[100:103], v[248:251], v[136:139], v[100:103]
.LBB0_699:
	s_or_b64 exec, exec, s[74:75]
	s_add_i32 s4, s30, -2
	v_cmp_ge_u32_e32 vcc, s4, v192
	v_cmp_lt_u32_e64 s[4:5], s19, v195
	s_and_b64 s[4:5], vcc, s[4:5]
	s_and_saveexec_b64 s[74:75], s[4:5]
	s_cbranch_execz .LBB0_733
	v_add_u32_e32 v251, 0x11700, v201
	v_add_u32_e32 v251, v251, v196
	ds_read_b32 v235, v251 offset:384
	ds_read_b32 v236, v251 offset:388
	ds_read_b32 v237, v251 offset:392
	ds_read_b32 v238, v251 offset:396
	ds_read_b32 v239, v251 offset:448
	ds_read_b32 v240, v251 offset:452
	ds_read_b32 v241, v251 offset:456
	ds_read_b32 v242, v251 offset:460
	ds_read_b32 v243, v251 offset:320
	ds_read_b32 v244, v251 offset:324
	ds_read_b32 v245, v251 offset:328
	ds_read_b32 v246, v251 offset:332
	ds_read_b32 v247, v251 offset:384
	ds_read_b32 v248, v251 offset:388
	ds_read_b32 v249, v251 offset:392
	ds_read_b32 v250, v251 offset:396
	ds_read_b128 v[140:143], v210
	ds_read_b128 v[132:135], v213 offset:13056
	ds_read_b128 v[226:229], v210 offset:64
	ds_read_b128 v[230:233], v213 offset:13120
	v_add_u32_e32 v1, 0xffffffad, v199
	v_cmp_gt_u32_e32 vcc, s53, v1
	v_add3_u32 v2, v201, v196, s88
	s_waitcnt lgkmcnt(3)
	v_mfma_f32_16x16x32_bf16 v[144:147], v[140:143], v[4:7], 0
	v_mfma_f32_16x16x32_bf16 v[140:143], v[140:143], v[20:23], 0
	s_waitcnt lgkmcnt(2)
	v_mfma_f32_16x16x32_bf16 v[136:139], v[132:135], v[20:23], 0
	v_mfma_f32_16x16x32_bf16 v[132:135], v[132:135], v[4:7], 0
	s_waitcnt lgkmcnt(1)
	v_mfma_f32_16x16x32_bf16 v[144:147], v[226:229], v[8:11], v[144:147]
	v_mfma_f32_16x16x32_bf16 v[140:143], v[226:229], v[24:27], v[140:143]
	ds_read_b128 v[226:229], v210 offset:128
	s_waitcnt lgkmcnt(1)
	v_mfma_f32_16x16x32_bf16 v[132:135], v[230:233], v[8:11], v[132:135]
	v_mfma_f32_16x16x32_bf16 v[136:139], v[230:233], v[24:27], v[136:139]
	ds_read_b128 v[230:233], v213 offset:13184
	s_waitcnt lgkmcnt(1)
	v_mfma_f32_16x16x32_bf16 v[144:147], v[226:229], v[12:15], v[144:147]
	v_mfma_f32_16x16x32_bf16 v[140:143], v[226:229], v[28:31], v[140:143]
	ds_read_b128 v[226:229], v210 offset:192
	s_waitcnt lgkmcnt(1)
	v_mfma_f32_16x16x32_bf16 v[132:135], v[230:233], v[12:15], v[132:135]
	v_mfma_f32_16x16x32_bf16 v[136:139], v[230:233], v[28:31], v[136:139]
	ds_read_b128 v[230:233], v213 offset:13248
	s_waitcnt lgkmcnt(1)
	v_mfma_f32_16x16x32_bf16 v[144:147], v[226:229], v[16:19], v[144:147]
	v_mfma_f32_16x16x32_bf16 v[140:143], v[226:229], v[32:35], v[140:143]
	s_waitcnt lgkmcnt(0)
	v_mfma_f32_16x16x32_bf16 v[132:135], v[230:233], v[16:19], v[132:135]
	v_mfma_f32_16x16x32_bf16 v[136:139], v[230:233], v[32:35], v[136:139]
	s_nop 2
	v_mov_b32_e32 v251, 0xf149f2ca
	s_waitcnt lgkmcnt(0)
	v_fmac_f32_e32 v235, 0x3e0293ee, v144
	v_cndmask_b32_e32 v229, v251, v235, vcc
	v_add_u32_e32 v1, 0xffffffae, v199
	v_cmp_gt_u32_e64 s[4:5], s53, v1
	v_add3_u32 v225, v201, v196, s55
	v_fmac_f32_e32 v236, 0x3e0293ee, v145
	v_cndmask_b32_e64 v228, v251, v236, s[4:5]
	v_add_u32_e32 v1, 0xffffffaf, v199
	v_cmp_gt_u32_e64 s[6:7], s53, v1
	v_add3_u32 v226, v201, v196, s59
	v_fmac_f32_e32 v237, 0x3e0293ee, v146
	v_cndmask_b32_e64 v230, v251, v237, s[6:7]
	v_add_u32_e32 v1, 0xffffffb0, v199
	v_cmp_gt_u32_e64 s[8:9], s53, v1
	v_add3_u32 v227, v201, v196, s43
	v_fmac_f32_e32 v238, 0x3e0293ee, v147
	v_cndmask_b32_e64 v145, v251, v238, s[8:9]
	v_add_u32_e32 v1, 0xffffffbd, v199
	v_cmp_gt_u32_e64 s[10:11], s53, v1
	v_fmac_f32_e32 v239, 0x3e0293ee, v132
	s_nop 0
	v_cndmask_b32_e64 v231, v251, v239, s[10:11]
	v_add_u32_e32 v1, 0xffffffbe, v199
	v_cmp_gt_u32_e64 s[10:11], s53, v1
	v_fmac_f32_e32 v240, 0x3e0293ee, v133
	s_nop 0
	v_cndmask_b32_e64 v232, v251, v240, s[10:11]
	v_add_u32_e32 v1, 0xffffffbf, v199
	v_cmp_gt_u32_e64 s[10:11], s53, v1
	v_fmac_f32_e32 v241, 0x3e0293ee, v134
	s_nop 0
	v_cndmask_b32_e64 v133, v251, v241, s[10:11]
	v_subrev_u32_e32 v1, 64, v199
	v_cmp_gt_u32_e64 s[10:11], s53, v1
	v_fmac_f32_e32 v242, 0x3e0293ee, v135
	s_nop 0
	v_cndmask_b32_e64 v132, v251, v242, s[10:11]
	v_mov_b32_e32 v144, 0xf149f2ca
	v_and_b32_e32 v134, 64, v182
	v_max3_f32 v1, v229, v144, v228
	v_xor_b32_e32 v3, 16, v182
	v_add_u32_e32 v134, 64, v134
	v_max3_f32 v1, v1, v230, v145
	v_cmp_lt_i32_e64 s[10:11], v3, v134
	v_max3_f32 v1, v1, v231, v232
	v_max3_f32 v1, v1, v133, v132
	v_cndmask_b32_e64 v3, v182, v3, s[10:11]
	v_lshlrev_b32_e32 v146, 2, v3
	v_mov_b32_e32 v253, v1
	v_mov_b32_e32 v135, v1
	s_nop 1
	v_permlane16_swap_b32_e32 v253, v135
	v_max_f32_e32 v135, v135, v253
	v_xor_b32_e32 v3, 32, v182
	v_cmp_lt_i32_e64 s[10:11], v3, v134
	s_waitcnt lgkmcnt(0)
; #define LAS __attribute__((address_space(3)))
; __device__ __forceinline__ unsigned cvt_pk_bf16(float lo, float hi) { unsigned r; asm volatile("v_cvt_pk_bf16_f32 %0, %1, %2" : "=v"(r) : "v"(lo), "v"(hi)); return r; }
; __device__ __forceinline__ void attn_unit(LAS unsigned char* lds, bf16_t* proj, const float* biasG, const float* sink, int s, int qb, int kh, int hp, bf16_t* dummy = nullptr) {
;     ...
;                 float sv[8]; float mx = -1e30f;
; #pragma unroll
;                 for (int kt = 0; kt < 2; ++kt)
; #pragma unroll
;                     for (int r = 0; r < 4; ++r) {
;                         const int kp = (kbi - 1) * 128 + si * 32 + kt * 16 + kg * 4 + r;
;                         const int rel = kp - qp; const bool valid = (rel >= -128) && (rel <= 128);
;                         const int idx = min(max(rel + 128, 0), 256);
;                         const float v = valid ? (sa[kt][qt][r] * SC + bL[hl * 260 + idx]) : -1e30f;
;                         sv[kt * 4 + r] = v; mx = fmaxf(mx, v);
;                     }
;                 mx = fmaxf(mx, __shfl_xor(mx, 16)); mx = fmaxf(mx, __shfl_xor(mx, 32));
;                 const float mnew = fmaxf(m2[qt], mx), alpha = __builtin_amdgcn_exp2f(m2[qt] - mnew); m2[qt] = mnew;
;                 float ps = 0.f; float pv[8];
; #pragma unroll
;                 for (int i = 0; i < 8; ++i) { pv[i] = __builtin_amdgcn_exp2f(sv[i] - mnew); ps += pv[i]; }
;                 lsum[qt] = lsum[qt] * alpha + ps;
; #pragma unroll
;                 for (int dt = 0; dt < 8; ++dt) o[dt][qt] = o[dt][qt] * alpha;
;                 u32x4 pw; pw.x = cvt_pk_bf16(pv[0], pv[1]); pw.y = cvt_pk_bf16(pv[2], pv[3]); pw.z = cvt_pk_bf16(pv[4], pv[5]); pw.w = cvt_pk_bf16(pv[6], pv[7]);
;                 pf[qt] = __builtin_bit_cast(bf16x8, pw);
;             }
; #pragma unroll
;             for (int dt = 0; dt < 8; ++dt) {
;                 const LAS unsigned char* vr = Vt + (dt * 16 + l16) * 288 + (si * 32 + kg * 4) * 2;
;                 const u32x2 lo = *(const LAS u32x2*)(vr), hi = *(const LAS u32x2*)(vr + 32);
	v_max_f32_e32 v134, v135, v135
	v_cndmask_b32_e64 v3, v182, v3, s[10:11]
	v_lshlrev_b32_e32 v3, 2, v3
	v_max_f32_e32 v1, v1, v134
	v_mov_b32_e32 v253, v1
	v_mov_b32_e32 v134, v1
	s_nop 1
	v_permlane32_swap_b32_e32 v253, v134
	v_max_f32_e32 v134, v134, v253
	s_waitcnt lgkmcnt(0)
	v_max3_f32 v1, v224, v1, v134
	v_sub_f32_e32 v134, v229, v1
	v_exp_f32_e32 v147, v134
	v_sub_f32_e32 v134, v228, v1
	v_exp_f32_e32 v228, v134
	v_sub_f32_e32 v134, v230, v1
	v_exp_f32_e32 v229, v134
	v_sub_f32_e32 v134, v145, v1
	v_exp_f32_e32 v230, v134
	v_sub_f32_e32 v134, v231, v1
	v_exp_f32_e32 v231, v134
	v_sub_f32_e32 v134, v232, v1
	v_sub_f32_e32 v133, v133, v1
	v_sub_f32_e32 v132, v132, v1
	v_exp_f32_e32 v232, v134
	v_exp_f32_e32 v233, v133
	v_exp_f32_e32 v234, v132
	v_add_u32_e32 v145, 0xffffff9d, v199
	v_cmp_gt_u32_e64 s[10:11], s53, v145
	v_cvt_pk_bf16_f32 v132, v147, v228
	v_cvt_pk_bf16_f32 v133, v229, v230
	v_cvt_pk_bf16_f32 v134, v231, v232
	v_cvt_pk_bf16_f32 v135, v233, v234
	v_fmac_f32_e32 v243, 0x3e0293ee, v140
	v_cndmask_b32_e64 v145, v251, v243, s[10:11]
	v_add_u32_e32 v140, 0xffffff9e, v199
	v_cmp_gt_u32_e64 s[10:11], s53, v140
	v_fmac_f32_e32 v244, 0x3e0293ee, v141
	s_nop 0
	v_cndmask_b32_e64 v144, v144, v244, s[10:11]
	v_add_u32_e32 v140, 0xffffff9f, v199
	v_cmp_gt_u32_e64 s[10:11], s53, v140
	v_fmac_f32_e32 v245, 0x3e0293ee, v142
	s_nop 0
	v_cndmask_b32_e64 v141, v251, v245, s[10:11]
	v_add_u32_e32 v142, 0xffffffa0, v199
	v_cmp_gt_u32_e64 s[10:11], s53, v142
	v_fmac_f32_e32 v246, 0x3e0293ee, v143
	s_nop 0
	v_cndmask_b32_e64 v140, v251, v246, s[10:11]
	v_fmac_f32_e32 v247, 0x3e0293ee, v136
	v_cndmask_b32_e32 v143, v251, v247, vcc
	v_fmac_f32_e32 v248, 0x3e0293ee, v137
	v_cndmask_b32_e64 v142, v251, v248, s[4:5]
	v_fmac_f32_e32 v249, 0x3e0293ee, v138
	v_cndmask_b32_e64 v137, v251, v249, s[6:7]
	v_fmac_f32_e32 v250, 0x3e0293ee, v139
	v_cndmask_b32_e64 v136, v251, v250, s[8:9]
	v_max3_f32 v2, v145, s89, v144
	v_max3_f32 v2, v2, v141, v140
	v_max3_f32 v139, v2, v143, v142
	v_add_f32_e32 v2, 0, v147
	v_add_f32_e32 v2, v228, v2
	v_add_f32_e32 v2, v229, v2
	v_sub_f32_e32 v138, v224, v1
	v_add_f32_e32 v2, v230, v2
	v_add_f32_e32 v2, v231, v2
	v_exp_f32_e32 v138, v138
	v_add_f32_e32 v2, v232, v2
	v_add_f32_e32 v2, v233, v2
	v_add_f32_e32 v2, v234, v2
	v_fmac_f32_e32 v2, v223, v138
	v_pk_mul_f32 v[98:99], v[98:99], v[138:139] op_sel_hi:[1,0]
	v_pk_mul_f32 v[96:97], v[96:97], v[138:139] op_sel_hi:[1,0]
	v_pk_mul_f32 v[106:107], v[106:107], v[138:139] op_sel_hi:[1,0]
	v_pk_mul_f32 v[104:105], v[104:105], v[138:139] op_sel_hi:[1,0]
	v_pk_mul_f32 v[110:111], v[110:111], v[138:139] op_sel_hi:[1,0]
	v_pk_mul_f32 v[108:109], v[108:109], v[138:139] op_sel_hi:[1,0]
	v_pk_mul_f32 v[114:115], v[114:115], v[138:139] op_sel_hi:[1,0]
	v_pk_mul_f32 v[112:113], v[112:113], v[138:139] op_sel_hi:[1,0]
	v_pk_mul_f32 v[118:119], v[118:119], v[138:139] op_sel_hi:[1,0]
	v_pk_mul_f32 v[116:117], v[116:117], v[138:139] op_sel_hi:[1,0]
	v_pk_mul_f32 v[122:123], v[122:123], v[138:139] op_sel_hi:[1,0]
	v_pk_mul_f32 v[120:121], v[120:121], v[138:139] op_sel_hi:[1,0]
	v_pk_mul_f32 v[126:127], v[126:127], v[138:139] op_sel_hi:[1,0]
	v_pk_mul_f32 v[124:125], v[124:125], v[138:139] op_sel_hi:[1,0]
	v_pk_mul_f32 v[130:131], v[130:131], v[138:139] op_sel_hi:[1,0]
	v_pk_mul_f32 v[128:129], v[128:129], v[138:139] op_sel_hi:[1,0]
	v_max3_f32 v138, v139, v137, v136
	v_mov_b32_e32 v253, v138
	v_mov_b32_e32 v139, v138
	s_nop 1
	v_permlane16_swap_b32_e32 v253, v139
	v_max_f32_e32 v139, v139, v253
	v_mov_b32_e32 v223, v2
	v_mov_b32_e32 v224, v1
	s_waitcnt lgkmcnt(0)
	v_max_f32_e32 v139, v139, v139
	v_max_f32_e32 v138, v138, v139
	v_mov_b32_e32 v253, v138
	v_mov_b32_e32 v3, v138
	s_nop 1
	v_permlane32_swap_b32_e32 v253, v3
	v_max_f32_e32 v3, v3, v253
	s_waitcnt lgkmcnt(0)
	v_max3_f32 v3, v222, v138, v3
	v_sub_f32_e32 v139, v145, v3
	v_exp_f32_e32 v139, v139
	v_sub_f32_e32 v144, v144, v3
	v_exp_f32_e32 v144, v144
	v_sub_f32_e32 v141, v141, v3
	v_exp_f32_e32 v141, v141
	v_sub_f32_e32 v140, v140, v3
	v_exp_f32_e32 v146, v140
	v_add_f32_e32 v145, 0, v139
	v_sub_f32_e32 v143, v143, v3
	v_add_f32_e32 v145, v144, v145
	v_exp_f32_e32 v143, v143
	v_sub_f32_e32 v142, v142, v3
	v_add_f32_e32 v145, v141, v145
	v_exp_f32_e32 v142, v142
	v_sub_f32_e32 v137, v137, v3
	v_add_f32_e32 v140, v146, v145
	v_exp_f32_e32 v145, v137
	v_sub_f32_e32 v136, v136, v3
	v_sub_f32_e32 v138, v222, v3
	v_exp_f32_e32 v147, v136
	v_add_f32_e32 v140, v143, v140
	v_exp_f32_e32 v136, v138
	v_add_f32_e32 v140, v142, v140
	v_add_f32_e32 v137, v145, v140
	v_add_f32_e32 v140, v147, v137
	v_fmac_f32_e32 v140, v221, v136
	v_pk_mul_f32 v[70:71], v[70:71], v[136:137] op_sel_hi:[1,0]
	v_pk_mul_f32 v[68:69], v[68:69], v[136:137] op_sel_hi:[1,0]
	v_pk_mul_f32 v[74:75], v[74:75], v[136:137] op_sel_hi:[1,0]
	v_pk_mul_f32 v[72:73], v[72:73], v[136:137] op_sel_hi:[1,0]
	v_pk_mul_f32 v[78:79], v[78:79], v[136:137] op_sel_hi:[1,0]
	v_pk_mul_f32 v[76:77], v[76:77], v[136:137] op_sel_hi:[1,0]
	v_pk_mul_f32 v[82:83], v[82:83], v[136:137] op_sel_hi:[1,0]
	v_pk_mul_f32 v[80:81], v[80:81], v[136:137] op_sel_hi:[1,0]
	v_pk_mul_f32 v[86:87], v[86:87], v[136:137] op_sel_hi:[1,0]
	v_pk_mul_f32 v[84:85], v[84:85], v[136:137] op_sel_hi:[1,0]
	v_pk_mul_f32 v[90:91], v[90:91], v[136:137] op_sel_hi:[1,0]
	v_pk_mul_f32 v[88:89], v[88:89], v[136:137] op_sel_hi:[1,0]
	v_pk_mul_f32 v[94:95], v[94:95], v[136:137] op_sel_hi:[1,0]
	v_pk_mul_f32 v[92:93], v[92:93], v[136:137] op_sel_hi:[1,0]
	v_pk_mul_f32 v[102:103], v[102:103], v[136:137] op_sel_hi:[1,0]
	v_pk_mul_f32 v[100:101], v[100:101], v[136:137] op_sel_hi:[1,0]
	v_cvt_pk_bf16_f32 v136, v139, v144
	v_cvt_pk_bf16_f32 v137, v141, v146
	v_add_u32_e32 v141, v197, v198
	v_cvt_pk_bf16_f32 v138, v143, v142
	v_add_u32_e32 v142, 0x8800, v141
	v_cvt_pk_bf16_f32 v139, v145, v147
	ds_read2_b64 v[236:239], v142 offset0:8 offset1:12
	v_mov_b32_e32 v221, v140
	v_add_u32_e32 v252, 0x9800, v141
	ds_read2_b64 v[240:243], v252 offset0:72 offset1:76
	ds_read2_b64 v[244:247], v215 offset0:8 offset1:12
	v_add_u32_e32 v252, 0xb800, v141
	ds_read2_b64 v[248:251], v252 offset0:200 offset1:204
	s_waitcnt lgkmcnt(3)
; __device__ __forceinline__ void attn_unit(LAS unsigned char* lds, bf16_t* proj, const float* biasG, const float* sink, int s, int qb, int kh, int hp, bf16_t* dummy = nullptr) {
;     ...
;             if (st < wq || st > wq + 8) continue;
;             f32x4 sa[2][2];
; #pragma unroll
;             for (int kt = 0; kt < 2; ++kt) { sa[kt][0] = (f32x4){0.f, 0.f, 0.f, 0.f}; sa[kt][1] = (f32x4){0.f, 0.f, 0.f, 0.f}; }
; #pragma unroll
;             for (int ks = 0; ks < 4; ++ks)
; #pragma unroll
;                 for (int kt = 0; kt < 2; ++kt) {
;                     const bf16x8 kf = *(const LAS bf16x8*)(Ks + (si * 32 + kt * 16 + l16) * 272 + ks * 64 + kg * 16);
;                     sa[kt][0] = __builtin_amdgcn_mfma_f32_16x16x32_bf16(kf, qf[0][ks], sa[kt][0], 0, 0, 0);
;                     sa[kt][1] = __builtin_amdgcn_mfma_f32_16x16x32_bf16(kf, qf[1][ks], sa[kt][1], 0, 0, 0);
;                 }
;             bf16x8 pf[2];
; #pragma unroll
;             for (int qt = 0; qt < 2; ++qt) {
;                 const int qp = wq * 32 + qt * 16 + l16;
;                 float sv[8]; float mx = -1e30f;
; #pragma unroll
;                 for (int kt = 0; kt < 2; ++kt)
; #pragma unroll
;                     for (int r = 0; r < 4; ++r) {
;                         const int kp = (kbi - 1) * 128 + si * 32 + kt * 16 + kg * 4 + r;
;                         const int rel = kp - qp; const bool valid = (rel >= -128) && (rel <= 128);
;                         const int idx = min(max(rel + 128, 0), 256);
;                         const float v = valid ? (sa[kt][qt][r] * SC + bL[hl * 260 + idx]) : -1e30f;
;                         sv[kt * 4 + r] = v; mx = fmaxf(mx, v);
;                     }
;                 mx = fmaxf(mx, __shfl_xor(mx, 16)); mx = fmaxf(mx, __shfl_xor(mx, 32));
;     ...
;             for (int dt = 0; dt < 8; ++dt) {
;                 const LAS unsigned char* vr = Vt + (dt * 16 + l16) * 288 + (si * 32 + kg * 4) * 2;
;                 const u32x2 lo = *(const LAS u32x2*)(vr), hi = *(const LAS u32x2*)(vr + 32);
;                 u32x4 vw; vw.x = lo.x; vw.y = lo.y; vw.z = hi.x; vw.w = hi.y;
;                 const bf16x8 vf = __builtin_bit_cast(bf16x8, vw);
;                 o[dt][0] = __builtin_amdgcn_mfma_f32_16x16x32_bf16(vf, pf[0], o[dt][0], 0, 0, 0);
;                 o[dt][1] = __builtin_amdgcn_mfma_f32_16x16x32_bf16(vf, pf[1], o[dt][1], 0, 0, 0);
;             }
	v_mfma_f32_16x16x32_bf16 v[96:99], v[236:239], v[132:135], v[96:99]
	v_mov_b32_e32 v222, v3
	v_mfma_f32_16x16x32_bf16 v[68:71], v[236:239], v[136:139], v[68:71]
	v_add_u32_e32 v252, 0xd000, v141
	ds_read2_b64 v[236:239], v252 offset0:8 offset1:12
	s_waitcnt lgkmcnt(3)
	v_mfma_f32_16x16x32_bf16 v[104:107], v[240:243], v[132:135], v[104:107]
	v_mfma_f32_16x16x32_bf16 v[72:75], v[240:243], v[136:139], v[72:75]
	v_add_u32_e32 v252, 0xe000, v141
	ds_read2_b64 v[240:243], v252 offset0:72 offset1:76
	v_add_u32_e32 v141, 0xf000, v141
	s_waitcnt lgkmcnt(3)
	v_mfma_f32_16x16x32_bf16 v[108:111], v[244:247], v[132:135], v[108:111]
	v_mfma_f32_16x16x32_bf16 v[76:79], v[244:247], v[136:139], v[76:79]
	ds_read2_b64 v[244:247], v141 offset0:136 offset1:140
	s_waitcnt lgkmcnt(3)
	v_mfma_f32_16x16x32_bf16 v[112:115], v[248:251], v[132:135], v[112:115]
	v_mfma_f32_16x16x32_bf16 v[80:83], v[248:251], v[136:139], v[80:83]
	ds_read2_b64 v[248:251], v216 offset0:192 offset1:196
	s_waitcnt lgkmcnt(3)
	v_mfma_f32_16x16x32_bf16 v[116:119], v[236:239], v[132:135], v[116:119]
	v_mfma_f32_16x16x32_bf16 v[84:87], v[236:239], v[136:139], v[84:87]
	s_waitcnt lgkmcnt(2)
	v_mfma_f32_16x16x32_bf16 v[120:123], v[240:243], v[132:135], v[120:123]
	v_mfma_f32_16x16x32_bf16 v[88:91], v[240:243], v[136:139], v[88:91]
	s_waitcnt lgkmcnt(1)
	v_mfma_f32_16x16x32_bf16 v[124:127], v[244:247], v[132:135], v[124:127]
	v_mfma_f32_16x16x32_bf16 v[92:95], v[244:247], v[136:139], v[92:95]
	s_waitcnt lgkmcnt(0)
	v_mfma_f32_16x16x32_bf16 v[128:131], v[248:251], v[132:135], v[128:131]
	v_mfma_f32_16x16x32_bf16 v[100:103], v[248:251], v[136:139], v[100:103]
.LBB0_733:
	s_or_b64 exec, exec, s[74:75]
	s_add_i32 s4, s30, -1
	v_cmp_ge_u32_e32 vcc, s4, v192
	v_cmp_le_u32_e64 s[4:5], s4, v195
	s_and_b64 s[4:5], vcc, s[4:5]
	s_and_saveexec_b64 s[74:75], s[4:5]
	s_cbranch_execz .LBB0_767
	v_add_u32_e32 v251, 0x11700, v201
	v_add_u32_e32 v251, v251, v196
	ds_read_b32 v235, v251 offset:512
	ds_read_b32 v236, v251 offset:516
	ds_read_b32 v237, v251 offset:520
	ds_read_b32 v238, v251 offset:524
	ds_read_b32 v239, v251 offset:576
	ds_read_b32 v240, v251 offset:580
	ds_read_b32 v241, v251 offset:584
	ds_read_b32 v242, v251 offset:588
	ds_read_b32 v243, v251 offset:448
	ds_read_b32 v244, v251 offset:452
	ds_read_b32 v245, v251 offset:456
	ds_read_b32 v246, v251 offset:460
	ds_read_b32 v247, v251 offset:512
	ds_read_b32 v248, v251 offset:516
	ds_read_b32 v249, v251 offset:520
	ds_read_b32 v250, v251 offset:524
	ds_read_b128 v[140:143], v211
	ds_read_b128 v[132:135], v213 offset:21760
	ds_read_b128 v[226:229], v211 offset:64
	ds_read_b128 v[230:233], v213 offset:21824
	v_subrev_u32_e32 v1, 51, v199
	v_cmp_gt_u32_e32 vcc, s53, v1
	v_add3_u32 v2, v201, v196, s14
	s_waitcnt lgkmcnt(3)
	v_mfma_f32_16x16x32_bf16 v[144:147], v[140:143], v[4:7], 0
	v_mfma_f32_16x16x32_bf16 v[140:143], v[140:143], v[20:23], 0
	s_waitcnt lgkmcnt(2)
	v_mfma_f32_16x16x32_bf16 v[136:139], v[132:135], v[20:23], 0
	v_mfma_f32_16x16x32_bf16 v[132:135], v[132:135], v[4:7], 0
	s_waitcnt lgkmcnt(1)
	v_mfma_f32_16x16x32_bf16 v[144:147], v[226:229], v[8:11], v[144:147]
	v_mfma_f32_16x16x32_bf16 v[140:143], v[226:229], v[24:27], v[140:143]
	ds_read_b128 v[226:229], v211 offset:128
	s_waitcnt lgkmcnt(1)
	v_mfma_f32_16x16x32_bf16 v[132:135], v[230:233], v[8:11], v[132:135]
	v_mfma_f32_16x16x32_bf16 v[136:139], v[230:233], v[24:27], v[136:139]
	ds_read_b128 v[230:233], v213 offset:21888
	s_waitcnt lgkmcnt(1)
	v_mfma_f32_16x16x32_bf16 v[144:147], v[226:229], v[12:15], v[144:147]
	v_mfma_f32_16x16x32_bf16 v[140:143], v[226:229], v[28:31], v[140:143]
	ds_read_b128 v[226:229], v211 offset:192
	s_waitcnt lgkmcnt(1)
	v_mfma_f32_16x16x32_bf16 v[132:135], v[230:233], v[12:15], v[132:135]
	v_mfma_f32_16x16x32_bf16 v[136:139], v[230:233], v[28:31], v[136:139]
	ds_read_b128 v[230:233], v213 offset:21952
	s_waitcnt lgkmcnt(1)
	v_mfma_f32_16x16x32_bf16 v[144:147], v[226:229], v[16:19], v[144:147]
	v_mfma_f32_16x16x32_bf16 v[140:143], v[226:229], v[32:35], v[140:143]
	s_waitcnt lgkmcnt(0)
	v_mfma_f32_16x16x32_bf16 v[132:135], v[230:233], v[16:19], v[132:135]
	v_mfma_f32_16x16x32_bf16 v[136:139], v[230:233], v[32:35], v[136:139]
	s_nop 2
	v_mov_b32_e32 v251, 0xf149f2ca
	s_waitcnt lgkmcnt(0)
	v_fmac_f32_e32 v235, 0x3e0293ee, v144
	v_cndmask_b32_e32 v229, v251, v235, vcc
	v_subrev_u32_e32 v1, 50, v199
	v_cmp_gt_u32_e64 s[4:5], s53, v1
	v_add3_u32 v225, v201, v196, s54
	v_fmac_f32_e32 v236, 0x3e0293ee, v145
	v_cndmask_b32_e64 v228, v251, v236, s[4:5]
	v_subrev_u32_e32 v1, 49, v199
	v_cmp_gt_u32_e64 s[6:7], s53, v1
	v_add3_u32 v226, v201, v196, s58
	v_fmac_f32_e32 v237, 0x3e0293ee, v146
	v_cndmask_b32_e64 v230, v251, v237, s[6:7]
	v_subrev_u32_e32 v1, 48, v199
	v_cmp_gt_u32_e64 s[8:9], s53, v1
	v_add3_u32 v227, v201, v196, s97
	v_fmac_f32_e32 v238, 0x3e0293ee, v147
	v_cndmask_b32_e64 v145, v251, v238, s[8:9]
	v_subrev_u32_e32 v1, 35, v199
	v_cmp_gt_u32_e64 s[10:11], s53, v1
	v_fmac_f32_e32 v239, 0x3e0293ee, v132
	s_nop 0
	v_cndmask_b32_e64 v231, v251, v239, s[10:11]
	v_subrev_u32_e32 v1, 34, v199
	v_cmp_gt_u32_e64 s[10:11], s53, v1
	v_fmac_f32_e32 v240, 0x3e0293ee, v133
	s_nop 0
	v_cndmask_b32_e64 v232, v251, v240, s[10:11]
	v_subrev_u32_e32 v1, 33, v199
	v_cmp_gt_u32_e64 s[10:11], s53, v1
	v_fmac_f32_e32 v241, 0x3e0293ee, v134
	s_nop 0
	v_cndmask_b32_e64 v133, v251, v241, s[10:11]
	v_subrev_u32_e32 v1, 32, v199
	v_cmp_gt_u32_e64 s[10:11], s53, v1
	v_fmac_f32_e32 v242, 0x3e0293ee, v135
	s_nop 0
	v_cndmask_b32_e64 v132, v251, v242, s[10:11]
	v_mov_b32_e32 v144, 0xf149f2ca
	v_and_b32_e32 v134, 64, v182
	v_max3_f32 v1, v229, v144, v228
	v_xor_b32_e32 v3, 16, v182
	v_add_u32_e32 v134, 64, v134
	v_max3_f32 v1, v1, v230, v145
	v_cmp_lt_i32_e64 s[10:11], v3, v134
	v_max3_f32 v1, v1, v231, v232
	v_max3_f32 v1, v1, v133, v132
	v_cndmask_b32_e64 v3, v182, v3, s[10:11]
	v_lshlrev_b32_e32 v146, 2, v3
	v_mov_b32_e32 v253, v1
	v_mov_b32_e32 v135, v1
	s_nop 1
	v_permlane16_swap_b32_e32 v253, v135
	v_max_f32_e32 v135, v135, v253
	v_xor_b32_e32 v3, 32, v182
	v_cmp_lt_i32_e64 s[10:11], v3, v134
	s_waitcnt lgkmcnt(0)
; #define LAS __attribute__((address_space(3)))
; __device__ __forceinline__ unsigned cvt_pk_bf16(float lo, float hi) { unsigned r; asm volatile("v_cvt_pk_bf16_f32 %0, %1, %2" : "=v"(r) : "v"(lo), "v"(hi)); return r; }
; __device__ __forceinline__ void attn_unit(LAS unsigned char* lds, bf16_t* proj, const float* biasG, const float* sink, int s, int qb, int kh, int hp, bf16_t* dummy = nullptr) {
;     ...
;                 float sv[8]; float mx = -1e30f;
; #pragma unroll
;                 for (int kt = 0; kt < 2; ++kt)
; #pragma unroll
;                     for (int r = 0; r < 4; ++r) {
;                         const int kp = (kbi - 1) * 128 + si * 32 + kt * 16 + kg * 4 + r;
;                         const int rel = kp - qp; const bool valid = (rel >= -128) && (rel <= 128);
;                         const int idx = min(max(rel + 128, 0), 256);
;                         const float v = valid ? (sa[kt][qt][r] * SC + bL[hl * 260 + idx]) : -1e30f;
;                         sv[kt * 4 + r] = v; mx = fmaxf(mx, v);
;                     }
;                 mx = fmaxf(mx, __shfl_xor(mx, 16)); mx = fmaxf(mx, __shfl_xor(mx, 32));
;                 const float mnew = fmaxf(m2[qt], mx), alpha = __builtin_amdgcn_exp2f(m2[qt] - mnew); m2[qt] = mnew;
;                 float ps = 0.f; float pv[8];
; #pragma unroll
;                 for (int i = 0; i < 8; ++i) { pv[i] = __builtin_amdgcn_exp2f(sv[i] - mnew); ps += pv[i]; }
;                 lsum[qt] = lsum[qt] * alpha + ps;
; #pragma unroll
;                 for (int dt = 0; dt < 8; ++dt) o[dt][qt] = o[dt][qt] * alpha;
;                 u32x4 pw; pw.x = cvt_pk_bf16(pv[0], pv[1]); pw.y = cvt_pk_bf16(pv[2], pv[3]); pw.z = cvt_pk_bf16(pv[4], pv[5]); pw.w = cvt_pk_bf16(pv[6], pv[7]);
;                 pf[qt] = __builtin_bit_cast(bf16x8, pw);
;             }
; #pragma unroll
;             for (int dt = 0; dt < 8; ++dt) {
;                 const LAS unsigned char* vr = Vt + (dt * 16 + l16) * 288 + (si * 32 + kg * 4) * 2;
;                 const u32x2 lo = *(const LAS u32x2*)(vr), hi = *(const LAS u32x2*)(vr + 32);
	v_max_f32_e32 v134, v135, v135
	v_cndmask_b32_e64 v3, v182, v3, s[10:11]
	v_lshlrev_b32_e32 v3, 2, v3
	v_max_f32_e32 v1, v1, v134
	v_mov_b32_e32 v253, v1
	v_mov_b32_e32 v134, v1
	s_nop 1
	v_permlane32_swap_b32_e32 v253, v134
	v_max_f32_e32 v134, v134, v253
	s_waitcnt lgkmcnt(0)
	v_max3_f32 v1, v224, v1, v134
	v_sub_f32_e32 v134, v229, v1
	v_exp_f32_e32 v147, v134
	v_sub_f32_e32 v134, v228, v1
	v_exp_f32_e32 v228, v134
	v_sub_f32_e32 v134, v230, v1
	v_exp_f32_e32 v229, v134
	v_sub_f32_e32 v134, v145, v1
	v_exp_f32_e32 v230, v134
	v_sub_f32_e32 v134, v231, v1
	v_exp_f32_e32 v231, v134
	v_sub_f32_e32 v134, v232, v1
	v_sub_f32_e32 v133, v133, v1
	v_sub_f32_e32 v132, v132, v1
	v_exp_f32_e32 v232, v134
	v_exp_f32_e32 v233, v133
	v_exp_f32_e32 v234, v132
	v_add_u32_e32 v145, 0xffffffbd, v199
	v_cmp_gt_u32_e64 s[10:11], s53, v145
	v_cvt_pk_bf16_f32 v132, v147, v228
	v_cvt_pk_bf16_f32 v133, v229, v230
	v_cvt_pk_bf16_f32 v134, v231, v232
	v_cvt_pk_bf16_f32 v135, v233, v234
	v_fmac_f32_e32 v243, 0x3e0293ee, v140
	v_cndmask_b32_e64 v145, v251, v243, s[10:11]
	v_add_u32_e32 v140, 0xffffffbe, v199
	v_cmp_gt_u32_e64 s[10:11], s53, v140
	v_fmac_f32_e32 v244, 0x3e0293ee, v141
	s_nop 0
	v_cndmask_b32_e64 v144, v144, v244, s[10:11]
	v_add_u32_e32 v140, 0xffffffbf, v199
	v_cmp_gt_u32_e64 s[10:11], s53, v140
	v_fmac_f32_e32 v245, 0x3e0293ee, v142
	s_nop 0
	v_cndmask_b32_e64 v141, v251, v245, s[10:11]
	v_subrev_u32_e32 v142, 64, v199
	v_cmp_gt_u32_e64 s[10:11], s53, v142
	v_fmac_f32_e32 v246, 0x3e0293ee, v143
	s_nop 0
	v_cndmask_b32_e64 v140, v251, v246, s[10:11]
	v_fmac_f32_e32 v247, 0x3e0293ee, v136
	v_cndmask_b32_e32 v143, v251, v247, vcc
	v_fmac_f32_e32 v248, 0x3e0293ee, v137
	v_cndmask_b32_e64 v142, v251, v248, s[4:5]
	v_fmac_f32_e32 v249, 0x3e0293ee, v138
	v_cndmask_b32_e64 v137, v251, v249, s[6:7]
	v_fmac_f32_e32 v250, 0x3e0293ee, v139
	v_cndmask_b32_e64 v136, v251, v250, s[8:9]
	v_max3_f32 v2, v145, s89, v144
	v_max3_f32 v2, v2, v141, v140
	v_max3_f32 v139, v2, v143, v142
	v_add_f32_e32 v2, 0, v147
	v_add_f32_e32 v2, v228, v2
	v_add_f32_e32 v2, v229, v2
	v_sub_f32_e32 v138, v224, v1
	v_add_f32_e32 v2, v230, v2
	v_add_f32_e32 v2, v231, v2
	v_exp_f32_e32 v138, v138
	v_add_f32_e32 v2, v232, v2
	v_add_f32_e32 v2, v233, v2
	v_add_f32_e32 v2, v234, v2
	v_fmac_f32_e32 v2, v223, v138
	v_pk_mul_f32 v[98:99], v[98:99], v[138:139] op_sel_hi:[1,0]
	v_pk_mul_f32 v[96:97], v[96:97], v[138:139] op_sel_hi:[1,0]
	v_pk_mul_f32 v[106:107], v[106:107], v[138:139] op_sel_hi:[1,0]
	v_pk_mul_f32 v[104:105], v[104:105], v[138:139] op_sel_hi:[1,0]
	v_pk_mul_f32 v[110:111], v[110:111], v[138:139] op_sel_hi:[1,0]
	v_pk_mul_f32 v[108:109], v[108:109], v[138:139] op_sel_hi:[1,0]
	v_pk_mul_f32 v[114:115], v[114:115], v[138:139] op_sel_hi:[1,0]
	v_pk_mul_f32 v[112:113], v[112:113], v[138:139] op_sel_hi:[1,0]
	v_pk_mul_f32 v[118:119], v[118:119], v[138:139] op_sel_hi:[1,0]
	v_pk_mul_f32 v[116:117], v[116:117], v[138:139] op_sel_hi:[1,0]
	v_pk_mul_f32 v[122:123], v[122:123], v[138:139] op_sel_hi:[1,0]
	v_pk_mul_f32 v[120:121], v[120:121], v[138:139] op_sel_hi:[1,0]
	v_pk_mul_f32 v[126:127], v[126:127], v[138:139] op_sel_hi:[1,0]
	v_pk_mul_f32 v[124:125], v[124:125], v[138:139] op_sel_hi:[1,0]
	v_pk_mul_f32 v[130:131], v[130:131], v[138:139] op_sel_hi:[1,0]
	v_pk_mul_f32 v[128:129], v[128:129], v[138:139] op_sel_hi:[1,0]
	v_max3_f32 v138, v139, v137, v136
	v_mov_b32_e32 v253, v138
	v_mov_b32_e32 v139, v138
	s_nop 1
	v_permlane16_swap_b32_e32 v253, v139
	v_max_f32_e32 v139, v139, v253
	v_mov_b32_e32 v223, v2
	v_mov_b32_e32 v224, v1
	s_waitcnt lgkmcnt(0)
	v_max_f32_e32 v139, v139, v139
	v_max_f32_e32 v138, v138, v139
	v_mov_b32_e32 v253, v138
	v_mov_b32_e32 v3, v138
	s_nop 1
	v_permlane32_swap_b32_e32 v253, v3
	v_max_f32_e32 v3, v3, v253
	s_waitcnt lgkmcnt(0)
	v_max3_f32 v3, v222, v138, v3
	v_sub_f32_e32 v139, v145, v3
	v_exp_f32_e32 v139, v139
	v_sub_f32_e32 v144, v144, v3
	v_exp_f32_e32 v144, v144
	v_sub_f32_e32 v141, v141, v3
	v_exp_f32_e32 v141, v141
	v_sub_f32_e32 v140, v140, v3
	v_exp_f32_e32 v146, v140
	v_add_f32_e32 v145, 0, v139
	v_sub_f32_e32 v143, v143, v3
	v_add_f32_e32 v145, v144, v145
	v_exp_f32_e32 v143, v143
	v_sub_f32_e32 v142, v142, v3
	v_add_f32_e32 v145, v141, v145
	v_exp_f32_e32 v142, v142
	v_sub_f32_e32 v137, v137, v3
	v_add_f32_e32 v140, v146, v145
	v_exp_f32_e32 v145, v137
	v_sub_f32_e32 v136, v136, v3
	v_sub_f32_e32 v138, v222, v3
	v_exp_f32_e32 v147, v136
	v_add_f32_e32 v140, v143, v140
	v_exp_f32_e32 v136, v138
	v_add_f32_e32 v140, v142, v140
	v_add_f32_e32 v137, v145, v140
	v_add_f32_e32 v140, v147, v137
	v_fmac_f32_e32 v140, v221, v136
	v_pk_mul_f32 v[70:71], v[70:71], v[136:137] op_sel_hi:[1,0]
	v_pk_mul_f32 v[68:69], v[68:69], v[136:137] op_sel_hi:[1,0]
	v_pk_mul_f32 v[74:75], v[74:75], v[136:137] op_sel_hi:[1,0]
	v_pk_mul_f32 v[72:73], v[72:73], v[136:137] op_sel_hi:[1,0]
	v_pk_mul_f32 v[78:79], v[78:79], v[136:137] op_sel_hi:[1,0]
	v_pk_mul_f32 v[76:77], v[76:77], v[136:137] op_sel_hi:[1,0]
	v_pk_mul_f32 v[82:83], v[82:83], v[136:137] op_sel_hi:[1,0]
	v_pk_mul_f32 v[80:81], v[80:81], v[136:137] op_sel_hi:[1,0]
	v_pk_mul_f32 v[86:87], v[86:87], v[136:137] op_sel_hi:[1,0]
	v_pk_mul_f32 v[84:85], v[84:85], v[136:137] op_sel_hi:[1,0]
	v_pk_mul_f32 v[90:91], v[90:91], v[136:137] op_sel_hi:[1,0]
	v_pk_mul_f32 v[88:89], v[88:89], v[136:137] op_sel_hi:[1,0]
	v_pk_mul_f32 v[94:95], v[94:95], v[136:137] op_sel_hi:[1,0]
	v_pk_mul_f32 v[92:93], v[92:93], v[136:137] op_sel_hi:[1,0]
	v_pk_mul_f32 v[102:103], v[102:103], v[136:137] op_sel_hi:[1,0]
	v_pk_mul_f32 v[100:101], v[100:101], v[136:137] op_sel_hi:[1,0]
	v_cvt_pk_bf16_f32 v136, v139, v144
	v_cvt_pk_bf16_f32 v137, v141, v146
	v_add_u32_e32 v141, v197, v198
	v_cvt_pk_bf16_f32 v138, v143, v142
	v_add_u32_e32 v142, 0x8800, v141
	v_cvt_pk_bf16_f32 v139, v145, v147
	ds_read2_b64 v[236:239], v142 offset0:16 offset1:20
	v_mov_b32_e32 v221, v140
	v_add_u32_e32 v252, 0x9800, v141
	ds_read2_b64 v[240:243], v252 offset0:80 offset1:84
	v_add_u32_e32 v252, 0xa800, v141
	ds_read2_b64 v[244:247], v252 offset0:144 offset1:148
	v_add_u32_e32 v252, 0xb800, v141
	ds_read2_b64 v[248:251], v252 offset0:208 offset1:212
	s_waitcnt lgkmcnt(3)
; #define LAS __attribute__((address_space(3)))
; __device__ __forceinline__ void attn_unit(LAS unsigned char* lds, bf16_t* proj, const float* biasG, const float* sink, int s, int qb, int kh, int hp, bf16_t* dummy = nullptr) {
;     ...
;             for (int dt = 0; dt < 8; ++dt) {
;                 const LAS unsigned char* vr = Vt + (dt * 16 + l16) * 288 + (si * 32 + kg * 4) * 2;
;                 const u32x2 lo = *(const LAS u32x2*)(vr), hi = *(const LAS u32x2*)(vr + 32);
;                 u32x4 vw; vw.x = lo.x; vw.y = lo.y; vw.z = hi.x; vw.w = hi.y;
;                 const bf16x8 vf = __builtin_bit_cast(bf16x8, vw);
;                 o[dt][0] = __builtin_amdgcn_mfma_f32_16x16x32_bf16(vf, pf[0], o[dt][0], 0, 0, 0);
;                 o[dt][1] = __builtin_amdgcn_mfma_f32_16x16x32_bf16(vf, pf[1], o[dt][1], 0, 0, 0);
;             }
	v_mfma_f32_16x16x32_bf16 v[96:99], v[236:239], v[132:135], v[96:99]
	v_mov_b32_e32 v222, v3
	v_mfma_f32_16x16x32_bf16 v[68:71], v[236:239], v[136:139], v[68:71]
	ds_read2_b64 v[236:239], v217 offset0:16 offset1:20
	s_waitcnt lgkmcnt(3)
	v_mfma_f32_16x16x32_bf16 v[104:107], v[240:243], v[132:135], v[104:107]
	v_mfma_f32_16x16x32_bf16 v[72:75], v[240:243], v[136:139], v[72:75]
	v_add_u32_e32 v252, 0xe000, v141
	ds_read2_b64 v[240:243], v252 offset0:80 offset1:84
	v_add_u32_e32 v141, 0xf000, v141
	s_waitcnt lgkmcnt(3)
	v_mfma_f32_16x16x32_bf16 v[108:111], v[244:247], v[132:135], v[108:111]
	v_mfma_f32_16x16x32_bf16 v[76:79], v[244:247], v[136:139], v[76:79]
	ds_read2_b64 v[244:247], v141 offset0:144 offset1:148
	s_waitcnt lgkmcnt(3)
	v_mfma_f32_16x16x32_bf16 v[112:115], v[248:251], v[132:135], v[112:115]
	v_mfma_f32_16x16x32_bf16 v[80:83], v[248:251], v[136:139], v[80:83]
	ds_read2_b64 v[248:251], v218 offset0:192 offset1:196
	s_waitcnt lgkmcnt(3)
	v_mfma_f32_16x16x32_bf16 v[116:119], v[236:239], v[132:135], v[116:119]
	v_mfma_f32_16x16x32_bf16 v[84:87], v[236:239], v[136:139], v[84:87]
	s_waitcnt lgkmcnt(2)
	v_mfma_f32_16x16x32_bf16 v[120:123], v[240:243], v[132:135], v[120:123]
	v_mfma_f32_16x16x32_bf16 v[88:91], v[240:243], v[136:139], v[88:91]
	s_waitcnt lgkmcnt(1)
	v_mfma_f32_16x16x32_bf16 v[124:127], v[244:247], v[132:135], v[124:127]
	v_mfma_f32_16x16x32_bf16 v[92:95], v[244:247], v[136:139], v[92:95]
	s_waitcnt lgkmcnt(0)
	v_mfma_f32_16x16x32_bf16 v[128:131], v[248:251], v[132:135], v[128:131]
	v_mfma_f32_16x16x32_bf16 v[100:103], v[248:251], v[136:139], v[100:103]
; #define LAS __attribute__((address_space(3)))
; __device__ __forceinline__ void attn_unit(LAS unsigned char* lds, bf16_t* proj, const float* biasG, const float* sink, int s, int qb, int kh, int hp, bf16_t* dummy = nullptr) {
;     ...
;         for (int si = 0; si < 4; ++si) {
;             const int st = kbi * 4 + si;
;             if (st < wq || st > wq + 8) continue;
;             f32x4 sa[2][2];
; #pragma unroll
;             for (int kt = 0; kt < 2; ++kt) { sa[kt][0] = (f32x4){0.f, 0.f, 0.f, 0.f}; sa[kt][1] = (f32x4){0.f, 0.f, 0.f, 0.f}; }
; #pragma unroll
;             for (int ks = 0; ks < 4; ++ks)
; #pragma unroll
;                 for (int kt = 0; kt < 2; ++kt) {
;                     const bf16x8 kf = *(const LAS bf16x8*)(Ks + (si * 32 + kt * 16 + l16) * 272 + ks * 64 + kg * 16);
;                     sa[kt][0] = __builtin_amdgcn_mfma_f32_16x16x32_bf16(kf, qf[0][ks], sa[kt][0], 0, 0, 0);
;                     sa[kt][1] = __builtin_amdgcn_mfma_f32_16x16x32_bf16(kf, qf[1][ks], sa[kt][1], 0, 0, 0);
;                 }
;             bf16x8 pf[2];
; #pragma unroll
;             for (int qt = 0; qt < 2; ++qt) {
;                 const int qp = wq * 32 + qt * 16 + l16;
;                 float sv[8]; float mx = -1e30f;
; #pragma unroll
;                 for (int kt = 0; kt < 2; ++kt)
; #pragma unroll
;                     for (int r = 0; r < 4; ++r) {
;                         const int kp = (kbi - 1) * 128 + si * 32 + kt * 16 + kg * 4 + r;
;                         const int rel = kp - qp; const bool valid = (rel >= -128) && (rel <= 128);
;                         const int idx = min(max(rel + 128, 0), 256);
;                         const float v = valid ? (sa[kt][qt][r] * SC + bL[hl * 260 + idx]) : -1e30f;
;                         sv[kt * 4 + r] = v; mx = fmaxf(mx, v);
;                     }
;                 mx = fmaxf(mx, __shfl_xor(mx, 16)); mx = fmaxf(mx, __shfl_xor(mx, 32));
;                 const float mnew = fmaxf(m2[qt], mx), alpha = __builtin_amdgcn_exp2f(m2[qt] - mnew); m2[qt] = mnew;
;                 float ps = 0.f; float pv[8];
; #pragma unroll
;                 for (int i = 0; i < 8; ++i) { pv[i] = __builtin_amdgcn_exp2f(sv[i] - mnew); ps += pv[i]; }
.LBB0_767:
	s_or_b64 exec, exec, s[74:75]
	v_cmp_le_u32_e32 vcc, s30, v195
	s_and_saveexec_b64 s[74:75], vcc
	s_cbranch_execz .LBB0_662
	v_add_u32_e32 v251, 0x11700, v201
	v_add_u32_e32 v251, v251, v196
	ds_read_b32 v235, v251 offset:640
	ds_read_b32 v236, v251 offset:644
	ds_read_b32 v237, v251 offset:648
	ds_read_b32 v238, v251 offset:652
	ds_read_b32 v239, v251 offset:704
	ds_read_b32 v240, v251 offset:708
	ds_read_b32 v241, v251 offset:712
	ds_read_b32 v242, v251 offset:716
	ds_read_b32 v243, v251 offset:576
	ds_read_b32 v244, v251 offset:580
	ds_read_b32 v245, v251 offset:584
	ds_read_b32 v246, v251 offset:588
	ds_read_b32 v247, v251 offset:640
	ds_read_b32 v248, v251 offset:644
	ds_read_b32 v249, v251 offset:648
	ds_read_b32 v250, v251 offset:652
	ds_read_b128 v[140:143], v212
	ds_read_b128 v[132:135], v213 offset:30464
	ds_read_b128 v[226:229], v212 offset:64
	ds_read_b128 v[230:233], v213 offset:30528
	v_subrev_u32_e32 v1, 19, v199
	v_cmp_gt_u32_e32 vcc, s53, v1
	v_add3_u32 v2, v201, v196, s49
	s_waitcnt lgkmcnt(3)
	v_mfma_f32_16x16x32_bf16 v[144:147], v[140:143], v[4:7], 0
	v_mfma_f32_16x16x32_bf16 v[140:143], v[140:143], v[20:23], 0
	s_waitcnt lgkmcnt(2)
	v_mfma_f32_16x16x32_bf16 v[136:139], v[132:135], v[20:23], 0
	v_mfma_f32_16x16x32_bf16 v[132:135], v[132:135], v[4:7], 0
	s_waitcnt lgkmcnt(1)
	v_mfma_f32_16x16x32_bf16 v[144:147], v[226:229], v[8:11], v[144:147]
	v_mfma_f32_16x16x32_bf16 v[140:143], v[226:229], v[24:27], v[140:143]
	ds_read_b128 v[226:229], v212 offset:128
	s_waitcnt lgkmcnt(1)
	v_mfma_f32_16x16x32_bf16 v[132:135], v[230:233], v[8:11], v[132:135]
	v_mfma_f32_16x16x32_bf16 v[136:139], v[230:233], v[24:27], v[136:139]
	ds_read_b128 v[230:233], v213 offset:30592
	s_waitcnt lgkmcnt(1)
	v_mfma_f32_16x16x32_bf16 v[144:147], v[226:229], v[12:15], v[144:147]
	v_mfma_f32_16x16x32_bf16 v[140:143], v[226:229], v[28:31], v[140:143]
	ds_read_b128 v[226:229], v212 offset:192
	s_waitcnt lgkmcnt(1)
	v_mfma_f32_16x16x32_bf16 v[132:135], v[230:233], v[12:15], v[132:135]
	v_mfma_f32_16x16x32_bf16 v[136:139], v[230:233], v[28:31], v[136:139]
	ds_read_b128 v[230:233], v213 offset:30656
	s_waitcnt lgkmcnt(1)
	v_mfma_f32_16x16x32_bf16 v[144:147], v[226:229], v[16:19], v[144:147]
	v_mfma_f32_16x16x32_bf16 v[140:143], v[226:229], v[32:35], v[140:143]
	s_waitcnt lgkmcnt(0)
	v_mfma_f32_16x16x32_bf16 v[132:135], v[230:233], v[16:19], v[132:135]
	v_mfma_f32_16x16x32_bf16 v[136:139], v[230:233], v[32:35], v[136:139]
	s_nop 2
	v_mov_b32_e32 v251, 0xf149f2ca
	s_waitcnt lgkmcnt(0)
	v_fmac_f32_e32 v235, 0x3e0293ee, v144
	v_cndmask_b32_e32 v229, v251, v235, vcc
	v_subrev_u32_e32 v1, 18, v199
	v_cmp_gt_u32_e64 s[4:5], s53, v1
	v_add3_u32 v225, v201, v196, s0
	v_fmac_f32_e32 v236, 0x3e0293ee, v145
	v_cndmask_b32_e64 v228, v251, v236, s[4:5]
	v_subrev_u32_e32 v1, 17, v199
	v_cmp_gt_u32_e64 s[6:7], s53, v1
	v_add3_u32 v226, v201, v196, s1
	v_fmac_f32_e32 v237, 0x3e0293ee, v146
	v_cndmask_b32_e64 v230, v251, v237, s[6:7]
	v_add_u32_e32 v1, -16, v199
	v_cmp_gt_u32_e64 s[8:9], s53, v1
	v_add3_u32 v227, v201, v196, s15
	v_fmac_f32_e32 v238, 0x3e0293ee, v147
	v_cndmask_b32_e64 v145, v251, v238, s[8:9]
	v_add_u32_e32 v1, -3, v199
	v_cmp_gt_u32_e64 s[10:11], s53, v1
	v_fmac_f32_e32 v239, 0x3e0293ee, v132
	s_nop 0
	v_cndmask_b32_e64 v231, v251, v239, s[10:11]
	v_add_u32_e32 v1, -2, v199
	v_cmp_gt_u32_e64 s[10:11], s53, v1
	v_fmac_f32_e32 v240, 0x3e0293ee, v133
	s_nop 0
	v_cndmask_b32_e64 v232, v251, v240, s[10:11]
	v_add_u32_e32 v1, -1, v199
	v_cmp_gt_u32_e64 s[10:11], s53, v1
	v_fmac_f32_e32 v241, 0x3e0293ee, v134
	s_nop 0
	v_cndmask_b32_e64 v133, v251, v241, s[10:11]
	v_cmp_gt_u32_e64 s[10:11], s53, v199
	v_fmac_f32_e32 v242, 0x3e0293ee, v135
	s_nop 0
	v_cndmask_b32_e64 v132, v251, v242, s[10:11]
	v_mov_b32_e32 v144, 0xf149f2ca
	v_and_b32_e32 v134, 64, v182
	v_max3_f32 v1, v229, v144, v228
	v_xor_b32_e32 v3, 16, v182
	v_add_u32_e32 v134, 64, v134
	v_max3_f32 v1, v1, v230, v145
	v_cmp_lt_i32_e64 s[10:11], v3, v134
	v_max3_f32 v1, v1, v231, v232
	v_max3_f32 v1, v1, v133, v132
	v_cndmask_b32_e64 v3, v182, v3, s[10:11]
	v_lshlrev_b32_e32 v146, 2, v3
	v_mov_b32_e32 v253, v1
	v_mov_b32_e32 v135, v1
	s_nop 1
	v_permlane16_swap_b32_e32 v253, v135
	v_max_f32_e32 v135, v135, v253
	v_xor_b32_e32 v3, 32, v182
	v_cmp_lt_i32_e64 s[10:11], v3, v134
	s_waitcnt lgkmcnt(0)
	v_max_f32_e32 v134, v135, v135
	v_cndmask_b32_e64 v3, v182, v3, s[10:11]
	v_lshlrev_b32_e32 v3, 2, v3
	v_max_f32_e32 v1, v1, v134
	v_mov_b32_e32 v253, v1
	v_mov_b32_e32 v134, v1
	s_nop 1
	v_permlane32_swap_b32_e32 v253, v134
	v_max_f32_e32 v134, v134, v253
	s_waitcnt lgkmcnt(0)
	v_max3_f32 v1, v224, v1, v134
	v_sub_f32_e32 v134, v229, v1
	v_exp_f32_e32 v147, v134
	v_sub_f32_e32 v134, v228, v1
	v_exp_f32_e32 v228, v134
	v_sub_f32_e32 v134, v230, v1
	v_exp_f32_e32 v229, v134
	v_sub_f32_e32 v134, v145, v1
	v_exp_f32_e32 v230, v134
	v_sub_f32_e32 v134, v231, v1
	v_exp_f32_e32 v231, v134
	v_sub_f32_e32 v134, v232, v1
	v_sub_f32_e32 v133, v133, v1
	v_sub_f32_e32 v132, v132, v1
	v_exp_f32_e32 v232, v134
	v_exp_f32_e32 v233, v133
	v_exp_f32_e32 v234, v132
	v_subrev_u32_e32 v145, 35, v199
	v_cmp_gt_u32_e64 s[10:11], s53, v145
	v_cvt_pk_bf16_f32 v132, v147, v228
	v_cvt_pk_bf16_f32 v133, v229, v230
	v_cvt_pk_bf16_f32 v134, v231, v232
	v_cvt_pk_bf16_f32 v135, v233, v234
	v_fmac_f32_e32 v243, 0x3e0293ee, v140
	v_cndmask_b32_e64 v145, v251, v243, s[10:11]
	v_subrev_u32_e32 v140, 34, v199
	v_cmp_gt_u32_e64 s[10:11], s53, v140
	v_fmac_f32_e32 v244, 0x3e0293ee, v141
	s_nop 0
	v_cndmask_b32_e64 v144, v144, v244, s[10:11]
	v_subrev_u32_e32 v140, 33, v199
	v_cmp_gt_u32_e64 s[10:11], s53, v140
	v_fmac_f32_e32 v245, 0x3e0293ee, v142
	s_nop 0
	v_cndmask_b32_e64 v141, v251, v245, s[10:11]
	v_subrev_u32_e32 v142, 32, v199
	v_cmp_gt_u32_e64 s[10:11], s53, v142
	v_fmac_f32_e32 v246, 0x3e0293ee, v143
	s_nop 0
	v_cndmask_b32_e64 v140, v251, v246, s[10:11]
	v_fmac_f32_e32 v247, 0x3e0293ee, v136
	v_cndmask_b32_e32 v143, v251, v247, vcc
	v_fmac_f32_e32 v248, 0x3e0293ee, v137
	v_cndmask_b32_e64 v142, v251, v248, s[4:5]
	v_mov_b32_e32 v136, 0xf149f2ca
	v_fmac_f32_e32 v249, 0x3e0293ee, v138
	v_cndmask_b32_e64 v137, v251, v249, s[6:7]
	s_and_saveexec_b64 s[4:5], s[8:9]
	s_cbranch_execz .LBB0_661
	v_mov_b32_e32 v136, v250
	v_fmac_f32_e32 v136, 0x3e0293ee, v139
	s_branch .LBB0_661
